# attention: 8-wide top-k rank loop, parallel chunk-list build; grid.sync replaced by XCD barrier; producer throttle; consumer priority
# speedup vs baseline: 1.0200x; 1.0200x over previous
.LBB0_152:
	v_readlane_b32 s0, v246, 25
	v_readlane_b32 s2, v245, 1
	v_ashrrev_i32_e32 v0, 4, v129
	v_mov_b32_e32 v1, s0
	v_readlane_b32 s0, v246, 23
	v_readlane_b32 s1, v246, 24
	s_mov_b32 s5, s70
	s_nop 0
	v_cndmask_b32_e64 v119, v129, v1, s[0:1]
	v_lshlrev_b32_e32 v1, 2, v119
	v_and_b32_e32 v2, 60, v1
	v_sub_u32_e32 v1, v129, v79
	v_sub_u32_e32 v4, 0, v1
	v_ashrrev_i32_e32 v3, 31, v1
	v_max_i32_e32 v1, v1, v4
	v_mul_hi_u32 v4, v1, v196
	v_mul_lo_u32 v5, v4, s2
	v_cndmask_b32_e64 v118, v0, v124, s[0:1]
	v_readlane_b32 s0, v245, 0
	v_sub_u32_e32 v1, v1, v5
	v_add_u32_e32 v5, 1, v4
	v_xor_b32_e32 v3, s0, v3
	v_cmp_le_u32_e64 s[0:1], s2, v1
	v_lshlrev_b32_e32 v0, 6, v118
	v_lshlrev_b32_e32 v116, 2, v2
	v_cndmask_b32_e64 v4, v4, v5, s[0:1]
	v_subrev_u32_e32 v5, s2, v1
	v_cndmask_b32_e64 v1, v1, v5, s[0:1]
	v_add_u32_e32 v5, 1, v4
	v_cmp_le_u32_e64 s[0:1], s2, v1
	s_nop 1
	v_cndmask_b32_e64 v1, v4, v5, s[0:1]
	v_xor_b32_e32 v1, v1, v3
	v_sub_u32_e32 v1, v1, v3
	s_movk_i32 s0, 0xab
	v_mul_lo_u32 v130, v1, s0
	v_ashrrev_i32_e32 v1, 31, v0
	s_and_saveexec_b64 s[0:1], vcc
	s_xor_b64 s[44:45], exec, s[0:1]
	s_cbranch_execz .LBB0_160
	v_lshl_add_u64 v[0:1], v[0:1], 2, s[64:65]
	v_mov_b32_e32 v117, v28
	v_lshl_add_u64 v[0:1], v[0:1], 0, v[116:117]
	s_waitcnt vmcnt(0)
	v_mov_b32_e32 v99, v28
	v_mov_b32_e32 v4, 0
	v_lshl_add_u64 v[16:17], v[0:1], 0, v[98:99]
	s_mov_b32 s72, 0
	v_mov_b32_e32 v5, v4
	v_mov_b32_e32 v6, v4
	v_mov_b32_e32 v7, v4
	v_mul_u32_u24_e32 v232, 0x110, v78
	v_lshl_add_u32 v232, v125, 2, v232
	v_mov_b32_e32 v19, v123
	v_mov_b32_e32 v24, v130
	ds_read_b32 v3, v19
	s_mov_b32 s73, 0
	s_mov_b32 s1, 0
	s_waitcnt lgkmcnt(0)
	s_setprio 3
	s_branch .LBB0_155

.LBB0_160:
	s_setprio 0
	s_mov_b32 s4, s60
	s_mov_b32 s60, s33
	s_mov_b32 s33, s74
	s_mov_b32 s74, s78
	s_andn2_saveexec_b64 s[2:3], s[44:45]
	s_cbranch_execz .LBB0_151
	v_lshlrev_b64 v[120:121], 2, v[0:1]
	v_lshl_add_u64 v[132:133], v[88:89], 0, v[120:121]
	v_mov_b32_e32 v117, v28
	v_add_u32_e32 v146, v120, v116
	v_add_u32_e32 v146, v146, v98
	v_lshrrev_b32_e32 v209, 4, v125
	v_mul_u32_u24_e32 v209, 0x460, v209
	s_movk_i32 s0, 0x110
	v_mad_u32_u24 v209, v78, s0, v209
	v_and_b32_e32 v243, 12, v125
	v_add_u32_e32 v209, v209, v243
	v_lshl_add_u32 v146, v126, 2, v146
	v_lshl_add_u64 v[108:109], v[90:91], 0, v[120:121]
	s_waitcnt vmcnt(0)
	v_lshlrev_b32_e32 v62, 2, v86
	v_mov_b32_e32 v63, v28
	v_mov_b32_e32 v101, v28
	v_mov_b32_e32 v103, v28
	v_mov_b32_e32 v105, v28
	v_lshl_add_u64 v[110:111], v[92:93], 0, v[120:121]
	v_lshl_add_u64 v[112:113], v[94:95], 0, v[120:121]
	v_lshl_add_u64 v[114:115], v[96:97], 0, v[120:121]
	v_lshl_add_u64 v[132:133], v[132:133], 0, v[116:117]
	v_mov_b32_e32 v107, v28
	v_lshl_add_u64 v[0:1], v[80:81], 0, v[120:121]
	v_lshl_add_u64 v[4:5], v[82:83], 0, v[120:121]
	v_lshl_add_u64 v[8:9], v[84:85], 0, v[120:121]
	v_lshl_add_u64 v[12:13], v[108:109], 0, v[62:63]
	v_lshl_add_u64 v[16:17], v[108:109], 0, v[100:101]
	v_lshl_add_u64 v[20:21], v[108:109], 0, v[102:103]
	v_lshl_add_u64 v[24:25], v[108:109], 0, v[104:105]
	v_lshl_add_u64 v[30:31], v[110:111], 0, v[62:63]
	v_lshl_add_u64 v[34:35], v[110:111], 0, v[100:101]
	v_lshl_add_u64 v[38:39], v[110:111], 0, v[102:103]
	v_lshl_add_u64 v[42:43], v[110:111], 0, v[104:105]
	v_lshl_add_u64 v[46:47], v[112:113], 0, v[62:63]
	v_lshl_add_u64 v[50:51], v[112:113], 0, v[100:101]
	v_lshl_add_u64 v[54:55], v[112:113], 0, v[102:103]
	v_lshl_add_u64 v[58:59], v[112:113], 0, v[104:105]
	v_lshl_add_u64 v[62:63], v[114:115], 0, v[62:63]
	v_lshl_add_u64 v[66:67], v[114:115], 0, v[100:101]
	v_lshl_add_u64 v[70:71], v[114:115], 0, v[102:103]
	v_lshl_add_u64 v[74:75], v[114:115], 0, v[104:105]
	v_lshl_add_u64 v[132:133], v[132:133], 0, v[106:107]
	global_load_dwordx4 v[0:3], v[0:1], off
	v_lshl_add_u64 v[120:121], s[62:63], 0, v[120:121]
	global_load_dwordx4 v[4:7], v[4:5], off
	v_lshl_add_u64 v[116:117], v[120:121], 0, v[116:117]
	global_load_dwordx4 v[8:11], v[8:9], off
	v_bitop3_b32 v101, v119, 15, v29 bitop3:0xc8
	v_ashrrev_i32_e32 v119, 31, v118
	v_lshl_add_u64 v[116:117], v[116:117], 0, v[106:107]
	v_readfirstlane_b32 s78, v29
	s_lshr_b32 s78, s78, 8
	v_cmp_eq_u32_e64 s[44:45], 0, v101
	v_lshl_add_u64 v[118:119], v[118:119], 2, s[48:49]
	s_lshl_b32 s0, s78, 15
	v_or_b32_e32 v20, s0, v86
	v_mov_b32_e32 v21, v28
	v_lshlrev_b64 v[62:63], 2, v[20:21]
	v_or_b32_e32 v14, 0x2000, v20
	v_mov_b32_e32 v15, v28
	v_or_b32_e32 v22, 0x4000, v20
	v_mov_b32_e32 v23, v28
	v_or_b32_e32 v20, 0x6000, v20
	v_lshlrev_b64 v[64:65], 2, v[14:15]
	v_lshlrev_b64 v[70:71], 2, v[22:23]
	v_lshlrev_b64 v[72:73], 2, v[20:21]
	v_lshl_add_u64 v[12:13], v[108:109], 0, v[62:63]
	v_lshl_add_u64 v[16:17], v[108:109], 0, v[64:65]
	v_lshl_add_u64 v[22:23], v[108:109], 0, v[70:71]
	v_lshl_add_u64 v[24:25], v[108:109], 0, v[72:73]
	v_lshl_add_u64 v[30:31], v[110:111], 0, v[62:63]
	v_lshl_add_u64 v[34:35], v[110:111], 0, v[64:65]
	v_lshl_add_u64 v[38:39], v[110:111], 0, v[70:71]
	v_lshl_add_u64 v[42:43], v[110:111], 0, v[72:73]
	v_lshl_add_u64 v[46:47], v[112:113], 0, v[62:63]
	v_lshl_add_u64 v[50:51], v[112:113], 0, v[64:65]
	v_lshl_add_u64 v[54:55], v[112:113], 0, v[70:71]
	v_lshl_add_u64 v[58:59], v[112:113], 0, v[72:73]
	v_lshl_add_u64 v[62:63], v[114:115], 0, v[62:63]
	v_lshl_add_u64 v[66:67], v[114:115], 0, v[64:65]
	v_lshl_add_u64 v[70:71], v[114:115], 0, v[70:71]
	v_lshl_add_u64 v[74:75], v[114:115], 0, v[72:73]
	v_or_b32_e32 v120, s0, v127
	v_mov_b32_e32 v121, v28
	global_load_dwordx4 v[12:15], v[12:13], off
	global_load_dwordx4 v[16:19], v[16:17], off
	global_load_dwordx4 v[20:23], v[22:23], off
	global_load_dwordx4 v[24:27], v[24:25], off
	global_load_dwordx4 v[30:33], v[30:31], off
	global_load_dwordx4 v[34:37], v[34:35], off
	global_load_dwordx4 v[38:41], v[38:39], off
	global_load_dwordx4 v[42:45], v[42:43], off
	global_load_dwordx4 v[46:49], v[46:47], off
	global_load_dwordx4 v[50:53], v[50:51], off
	global_load_dwordx4 v[54:57], v[54:55], off
	global_load_dwordx4 v[58:61], v[58:59], off
	global_load_dwordx4 v[62:65], v[62:63], off
	global_load_dwordx4 v[66:69], v[66:67], off
	global_load_dwordx4 v[70:73], v[70:71], off
	global_load_dwordx4 v[74:77], v[74:75], off
	v_lshl_add_u64 v[120:121], v[120:121], 2, v[116:117]
	global_load_dword v99, v[120:121], off
	s_add_i32 s0, s78, 2
	s_lshl_b32 s0, s0, 15
	v_or_b32_e32 v158, s0, v86
	v_mov_b32_e32 v159, v28
	v_lshlrev_b64 v[226:227], 2, v[158:159]
	v_or_b32_e32 v152, 0x2000, v158
	v_mov_b32_e32 v153, v28
	v_or_b32_e32 v160, 0x4000, v158
	v_mov_b32_e32 v161, v28
	v_or_b32_e32 v158, 0x6000, v158
	v_lshlrev_b64 v[228:229], 2, v[152:153]
	v_lshlrev_b64 v[234:235], 2, v[160:161]
	v_lshlrev_b64 v[236:237], 2, v[158:159]
	v_lshl_add_u64 v[150:151], v[108:109], 0, v[226:227]
	v_lshl_add_u64 v[154:155], v[108:109], 0, v[228:229]
	v_lshl_add_u64 v[160:161], v[108:109], 0, v[234:235]
	v_lshl_add_u64 v[162:163], v[108:109], 0, v[236:237]
	v_lshl_add_u64 v[166:167], v[110:111], 0, v[226:227]
	v_lshl_add_u64 v[170:171], v[110:111], 0, v[228:229]
	v_lshl_add_u64 v[174:175], v[110:111], 0, v[234:235]
	v_lshl_add_u64 v[178:179], v[110:111], 0, v[236:237]
	v_lshl_add_u64 v[210:211], v[112:113], 0, v[226:227]
	v_lshl_add_u64 v[214:215], v[112:113], 0, v[228:229]
	v_lshl_add_u64 v[218:219], v[112:113], 0, v[234:235]
	v_lshl_add_u64 v[222:223], v[112:113], 0, v[236:237]
	v_lshl_add_u64 v[226:227], v[114:115], 0, v[226:227]
	v_lshl_add_u64 v[230:231], v[114:115], 0, v[228:229]
	v_lshl_add_u64 v[234:235], v[114:115], 0, v[234:235]
	v_lshl_add_u64 v[238:239], v[114:115], 0, v[236:237]
	v_or_b32_e32 v120, s0, v127
	v_mov_b32_e32 v121, v28
	global_load_dwordx4 v[150:153], v[150:151], off
	global_load_dwordx4 v[154:157], v[154:155], off
	global_load_dwordx4 v[158:161], v[160:161], off
	global_load_dwordx4 v[162:165], v[162:163], off
	global_load_dwordx4 v[166:169], v[166:167], off
	global_load_dwordx4 v[170:173], v[170:171], off
	global_load_dwordx4 v[174:177], v[174:175], off
	global_load_dwordx4 v[178:181], v[178:179], off
	global_load_dwordx4 v[210:213], v[210:211], off
	global_load_dwordx4 v[214:217], v[214:215], off
	global_load_dwordx4 v[218:221], v[218:219], off
	global_load_dwordx4 v[222:225], v[222:223], off
	global_load_dwordx4 v[226:229], v[226:227], off
	global_load_dwordx4 v[230:233], v[230:231], off
	global_load_dwordx4 v[234:237], v[234:235], off
	global_load_dwordx4 v[238:241], v[238:239], off
	v_lshl_add_u64 v[120:121], v[120:121], 2, v[116:117]
	global_load_dword v242, v[120:121], off
	v_lshl_add_u32 v131, s78, 2, v123
	ds_read_b32 v105, v131 offset:16

.Lp4_a_go:
	s_nop 15
	s_nop 15
	s_nop 15
	s_nop 15
	s_nop 15
	s_nop 15
	s_nop 15
	s_nop 15
	s_nop 15
	s_nop 15
	s_nop 15
	s_nop 15
	s_nop 15
	s_nop 15
	s_nop 15
	s_nop 15
	s_nop 15
	s_nop 15
	s_nop 15
	s_nop 15
	s_or_b64 exec, exec, s[70:71]
	s_cmp_lt_u32 s78, 3
	s_cbranch_scc1 .Lp4_a_noyr
	s_mul_i32 s0, s87, 0x5100
	v_add3_u32 v131, v87, s0, v209
	ds_read_b32 v182, v131 offset:9216
	ds_read_b32 v183, v131 offset:9232
	ds_read_b32 v184, v131 offset:9248
	ds_read_b32 v185, v131 offset:9264
	ds_read_b32 v186, v131 offset:9280
	ds_read_b32 v187, v131 offset:9296
	ds_read_b32 v188, v131 offset:9312
	ds_read_b32 v189, v131 offset:9328
	ds_read_b32 v190, v131 offset:9344
	ds_read_b32 v191, v131 offset:9360
	ds_read_b32 v192, v131 offset:9376
	ds_read_b32 v193, v131 offset:9392
	ds_read_b32 v194, v131 offset:9408
	ds_read_b32 v195, v131 offset:9424
	ds_read_b32 v243, v131 offset:9440
	ds_read_b32 v147, v131 offset:9456

.LBB0_580:
	v_mad_i64_i32 v[0:1], s[0:1], v84, s84, v[152:153]
	flat_load_dword v2, v[0:1]
	v_lshl_add_u64 v[0:1], v[158:159], 0, v[86:87]
	v_add_u32_e32 v29, s18, v130
	s_waitcnt vmcnt(0) lgkmcnt(0)
	v_mul_f32_e32 v2, v166, v2
	v_pk_mul_f32 v[4:5], v[18:19], v[2:3] op_sel_hi:[1,0]
	v_pk_mul_f32 v[6:7], v[16:17], v[2:3] op_sel_hi:[1,0]
	v_pk_mul_f32 v[8:9], v[40:41], v[2:3] op_sel_hi:[1,0]
	v_pk_mul_f32 v[10:11], v[38:39], v[2:3] op_sel_hi:[1,0]
	v_cvt_pk_bf16_f32 v6, v6, v7
	v_cvt_pk_bf16_f32 v7, v4, v5
	flat_store_dwordx2 v[0:1], v[6:7]
	v_cvt_pk_bf16_f32 v4, v10, v11
	v_cvt_pk_bf16_f32 v5, v8, v9
	v_pk_mul_f32 v[12:13], v[44:45], v[2:3] op_sel_hi:[1,0]
	v_pk_mul_f32 v[14:15], v[42:43], v[2:3] op_sel_hi:[1,0]
	flat_store_dwordx2 v[0:1], v[4:5] offset:32
	v_cvt_pk_bf16_f32 v4, v14, v15
	v_cvt_pk_bf16_f32 v5, v12, v13
	v_pk_mul_f32 v[16:17], v[48:49], v[2:3] op_sel_hi:[1,0]
	v_pk_mul_f32 v[18:19], v[46:47], v[2:3] op_sel_hi:[1,0]
	flat_store_dwordx2 v[0:1], v[4:5] offset:64
	v_cvt_pk_bf16_f32 v4, v18, v19
	v_cvt_pk_bf16_f32 v5, v16, v17
	v_pk_mul_f32 v[20:21], v[52:53], v[2:3] op_sel_hi:[1,0]
	v_pk_mul_f32 v[22:23], v[50:51], v[2:3] op_sel_hi:[1,0]
	flat_store_dwordx2 v[0:1], v[4:5] offset:96
	v_cvt_pk_bf16_f32 v4, v22, v23
	v_cvt_pk_bf16_f32 v5, v20, v21
	v_pk_mul_f32 v[24:25], v[56:57], v[2:3] op_sel_hi:[1,0]
	v_pk_mul_f32 v[26:27], v[54:55], v[2:3] op_sel_hi:[1,0]
	v_pk_mul_f32 v[30:31], v[60:61], v[2:3] op_sel_hi:[1,0]
	v_pk_mul_f32 v[32:33], v[58:59], v[2:3] op_sel_hi:[1,0]
	v_pk_mul_f32 v[34:35], v[64:65], v[2:3] op_sel_hi:[1,0]
	v_pk_mul_f32 v[2:3], v[62:63], v[2:3] op_sel_hi:[1,0]
	flat_store_dwordx2 v[0:1], v[4:5] offset:128
	v_cvt_pk_bf16_f32 v4, v26, v27
	v_cvt_pk_bf16_f32 v5, v24, v25
	flat_store_dwordx2 v[0:1], v[4:5] offset:160
	v_cvt_pk_bf16_f32 v4, v32, v33
	v_cvt_pk_bf16_f32 v5, v30, v31
	flat_store_dwordx2 v[0:1], v[4:5] offset:192
	v_cvt_pk_bf16_f32 v2, v2, v3
	v_cvt_pk_bf16_f32 v3, v34, v35
	flat_store_dwordx2 v[0:1], v[2:3] offset:224
	s_waitcnt lgkmcnt(0)
	s_barrier
	ds_read2st64_b32 v[0:1], v139 offset0:44 offset1:45
	ds_read2st64_b32 v[4:5], v140 offset0:44 offset1:45
	ds_read2st64_b32 v[6:7], v141 offset0:44 offset1:45
	ds_read2st64_b32 v[8:9], v142 offset0:44 offset1:45
	v_ashrrev_i32_e32 v2, 6, v29
	v_cmp_lt_i32_e64 s[12:13], 15, v2
	s_waitcnt lgkmcnt(0)
	v_mov_b32_e32 v10, v1
	v_mov_b32_e32 v11, v0
	v_mov_b32_e32 v0, v5
	v_mov_b32_e32 v1, v4
	v_mov_b32_e32 v4, v7
	v_mov_b32_e32 v5, v6
	v_mov_b32_e32 v6, v9
	v_mov_b32_e32 v7, v8
	v_pk_add_f32 v[8:9], v[10:11], 0 op_sel_hi:[1,0]
	s_nop 0
	v_pk_add_f32 v[0:1], v[8:9], v[0:1]
	s_nop 0
	v_pk_add_f32 v[0:1], v[0:1], v[4:5]
	s_nop 0
	v_pk_add_f32 v[0:1], v[0:1], v[6:7]
	ds_write2st64_b32 v131, v1, v0 offset1:1
	s_and_saveexec_b64 s[2:3], s[12:13]
	s_xor_b64 s[2:3], exec, s[2:3]
	s_cbranch_execz .LBB0_584
	s_mov_b32 s7, 1
	v_mov_b32_e32 v3, 0
	s_mov_b64 s[20:21], 0
	v_mov_b32_e32 v5, v138
	v_mov_b32_e32 v4, 0
	v_readfirstlane_b32 s98, v2
	s_sub_i32 s98, s98, 9
.Lsel8_0_top:
	s_cmp_gt_i32 s7, s98
	s_cbranch_scc1 .LBB0_582
	ds_read2_b32 v[6:7], v5 offset1:1
	ds_read2_b32 v[8:9], v5 offset0:2 offset1:3
	ds_read2_b32 v[240:241], v5 offset0:4 offset1:5
	ds_read2_b32 v[242:243], v5 offset0:6 offset1:7
	v_add_u32_e32 v5, 32, v5
	s_waitcnt lgkmcnt(0)
	v_cmp_lt_u32_e64 s[0:1], s7, v155
	v_cmp_eq_f32_e64 s[18:19], v6, v1
	v_cmp_gt_f32_e32 vcc, v6, v1
	s_and_b64 s[0:1], s[18:19], s[0:1]
	s_or_b64 vcc, vcc, s[0:1]
	v_addc_co_u32_e32 v3, vcc, 0, v3, vcc
	v_cmp_eq_f32_e64 s[16:17], v6, v0
	v_cmp_lt_u32_e32 vcc, s7, v132
	v_cmp_gt_f32_e64 s[14:15], v6, v0
	s_and_b64 s[0:1], s[16:17], vcc
	s_or_b64 vcc, s[14:15], s[0:1]
	v_addc_co_u32_e32 v4, vcc, 0, v4, vcc
	s_add_i32 s99, s7, 1
	v_cmp_lt_u32_e64 s[0:1], s99, v155
	v_cmp_eq_f32_e64 s[18:19], v7, v1
	v_cmp_gt_f32_e32 vcc, v7, v1
	s_and_b64 s[0:1], s[18:19], s[0:1]
	s_or_b64 vcc, vcc, s[0:1]
	v_addc_co_u32_e32 v3, vcc, 0, v3, vcc
	v_cmp_eq_f32_e64 s[16:17], v7, v0
	v_cmp_lt_u32_e32 vcc, s99, v132
	v_cmp_gt_f32_e64 s[14:15], v7, v0
	s_and_b64 s[0:1], s[16:17], vcc
	s_or_b64 vcc, s[14:15], s[0:1]
	v_addc_co_u32_e32 v4, vcc, 0, v4, vcc
	s_add_i32 s99, s7, 2
	v_cmp_lt_u32_e64 s[0:1], s99, v155
	v_cmp_eq_f32_e64 s[18:19], v8, v1
	v_cmp_gt_f32_e32 vcc, v8, v1
	s_and_b64 s[0:1], s[18:19], s[0:1]
	s_or_b64 vcc, vcc, s[0:1]
	v_addc_co_u32_e32 v3, vcc, 0, v3, vcc
	v_cmp_eq_f32_e64 s[16:17], v8, v0
	v_cmp_lt_u32_e32 vcc, s99, v132
	v_cmp_gt_f32_e64 s[14:15], v8, v0
	s_and_b64 s[0:1], s[16:17], vcc
	s_or_b64 vcc, s[14:15], s[0:1]
	v_addc_co_u32_e32 v4, vcc, 0, v4, vcc
	s_add_i32 s99, s7, 3
	v_cmp_lt_u32_e64 s[0:1], s99, v155
	v_cmp_eq_f32_e64 s[18:19], v9, v1
	v_cmp_gt_f32_e32 vcc, v9, v1
	s_and_b64 s[0:1], s[18:19], s[0:1]
	s_or_b64 vcc, vcc, s[0:1]
	v_addc_co_u32_e32 v3, vcc, 0, v3, vcc
	v_cmp_eq_f32_e64 s[16:17], v9, v0
	v_cmp_lt_u32_e32 vcc, s99, v132
	v_cmp_gt_f32_e64 s[14:15], v9, v0
	s_and_b64 s[0:1], s[16:17], vcc
	s_or_b64 vcc, s[14:15], s[0:1]
	v_addc_co_u32_e32 v4, vcc, 0, v4, vcc
	s_add_i32 s99, s7, 4
	v_cmp_lt_u32_e64 s[0:1], s99, v155
	v_cmp_eq_f32_e64 s[18:19], v240, v1
	v_cmp_gt_f32_e32 vcc, v240, v1
	s_and_b64 s[0:1], s[18:19], s[0:1]
	s_or_b64 vcc, vcc, s[0:1]
	v_addc_co_u32_e32 v3, vcc, 0, v3, vcc
	v_cmp_eq_f32_e64 s[16:17], v240, v0
	v_cmp_lt_u32_e32 vcc, s99, v132
	v_cmp_gt_f32_e64 s[14:15], v240, v0
	s_and_b64 s[0:1], s[16:17], vcc
	s_or_b64 vcc, s[14:15], s[0:1]
	v_addc_co_u32_e32 v4, vcc, 0, v4, vcc
	s_add_i32 s99, s7, 5
	v_cmp_lt_u32_e64 s[0:1], s99, v155
	v_cmp_eq_f32_e64 s[18:19], v241, v1
	v_cmp_gt_f32_e32 vcc, v241, v1
	s_and_b64 s[0:1], s[18:19], s[0:1]
	s_or_b64 vcc, vcc, s[0:1]
	v_addc_co_u32_e32 v3, vcc, 0, v3, vcc
	v_cmp_eq_f32_e64 s[16:17], v241, v0
	v_cmp_lt_u32_e32 vcc, s99, v132
	v_cmp_gt_f32_e64 s[14:15], v241, v0
	s_and_b64 s[0:1], s[16:17], vcc
	s_or_b64 vcc, s[14:15], s[0:1]
	v_addc_co_u32_e32 v4, vcc, 0, v4, vcc
	s_add_i32 s99, s7, 6
	v_cmp_lt_u32_e64 s[0:1], s99, v155
	v_cmp_eq_f32_e64 s[18:19], v242, v1
	v_cmp_gt_f32_e32 vcc, v242, v1
	s_and_b64 s[0:1], s[18:19], s[0:1]
	s_or_b64 vcc, vcc, s[0:1]
	v_addc_co_u32_e32 v3, vcc, 0, v3, vcc
	v_cmp_eq_f32_e64 s[16:17], v242, v0
	v_cmp_lt_u32_e32 vcc, s99, v132
	v_cmp_gt_f32_e64 s[14:15], v242, v0
	s_and_b64 s[0:1], s[16:17], vcc
	s_or_b64 vcc, s[14:15], s[0:1]
	v_addc_co_u32_e32 v4, vcc, 0, v4, vcc
	s_add_i32 s99, s7, 7
	v_cmp_lt_u32_e64 s[0:1], s99, v155
	v_cmp_eq_f32_e64 s[18:19], v243, v1
	v_cmp_gt_f32_e32 vcc, v243, v1
	s_and_b64 s[0:1], s[18:19], s[0:1]
	s_or_b64 vcc, vcc, s[0:1]
	v_addc_co_u32_e32 v3, vcc, 0, v3, vcc
	v_cmp_eq_f32_e64 s[16:17], v243, v0
	v_cmp_lt_u32_e32 vcc, s99, v132
	v_cmp_gt_f32_e64 s[14:15], v243, v0
	s_and_b64 s[0:1], s[16:17], vcc
	s_or_b64 vcc, s[14:15], s[0:1]
	v_addc_co_u32_e32 v4, vcc, 0, v4, vcc
	s_add_i32 s7, s7, 8
	s_branch .Lsel8_0_top

.LBB0_588:
	s_or_b64 exec, exec, s[2:3]
	ds_read2st64_b32 v[0:1], v143 offset0:44 offset1:45
	ds_read2st64_b32 v[4:5], v144 offset0:44 offset1:45
	ds_read2st64_b32 v[6:7], v145 offset0:44 offset1:45
	ds_read2st64_b32 v[8:9], v146 offset0:44 offset1:45
	s_waitcnt lgkmcnt(0)
	v_mov_b32_e32 v10, v1
	v_mov_b32_e32 v11, v0
	v_pk_add_f32 v[0:1], v[10:11], 0 op_sel_hi:[1,0]
	v_mov_b32_e32 v10, v5
	v_mov_b32_e32 v11, v4
	v_pk_add_f32 v[0:1], v[0:1], v[10:11]
	v_mov_b32_e32 v4, v7
	v_mov_b32_e32 v5, v6
	v_pk_add_f32 v[0:1], v[0:1], v[4:5]
	v_mov_b32_e32 v4, v9
	v_mov_b32_e32 v5, v8
	v_pk_add_f32 v[0:1], v[0:1], v[4:5]
	ds_write2st64_b32 v131, v1, v0 offset1:1
	s_and_saveexec_b64 s[2:3], s[12:13]
	s_xor_b64 s[2:3], exec, s[2:3]
	s_cbranch_execz .LBB0_592
	s_mov_b32 s72, 1
	v_mov_b32_e32 v3, 0
	s_mov_b64 s[38:39], 0
	v_mov_b32_e32 v5, v138
	v_mov_b32_e32 v4, 0
	v_readfirstlane_b32 s98, v2
	s_sub_i32 s98, s98, 9
.Lsel8_1_top:
	s_cmp_gt_i32 s72, s98
	s_cbranch_scc1 .LBB0_590
	ds_read2_b32 v[6:7], v5 offset1:1
	ds_read2_b32 v[8:9], v5 offset0:2 offset1:3
	ds_read2_b32 v[240:241], v5 offset0:4 offset1:5
	ds_read2_b32 v[242:243], v5 offset0:6 offset1:7
	v_add_u32_e32 v5, 32, v5
	s_waitcnt lgkmcnt(0)
	v_cmp_lt_u32_e64 s[14:15], s72, v155
	v_cmp_eq_f32_e64 s[20:21], v6, v1
	v_cmp_gt_f32_e64 s[0:1], v6, v1
	s_and_b64 s[14:15], s[20:21], s[14:15]
	s_or_b64 s[0:1], s[0:1], s[14:15]
	v_addc_co_u32_e64 v3, s[0:1], 0, v3, s[0:1]
	v_cmp_eq_f32_e64 s[18:19], v6, v0
	v_cmp_lt_u32_e64 s[0:1], s72, v132
	v_cmp_gt_f32_e64 s[16:17], v6, v0
	s_and_b64 s[0:1], s[18:19], s[0:1]
	s_or_b64 s[0:1], s[16:17], s[0:1]
	v_addc_co_u32_e64 v4, s[0:1], 0, v4, s[0:1]
	s_add_i32 s99, s72, 1
	v_cmp_lt_u32_e64 s[14:15], s99, v155
	v_cmp_eq_f32_e64 s[20:21], v7, v1
	v_cmp_gt_f32_e64 s[0:1], v7, v1
	s_and_b64 s[14:15], s[20:21], s[14:15]
	s_or_b64 s[0:1], s[0:1], s[14:15]
	v_addc_co_u32_e64 v3, s[0:1], 0, v3, s[0:1]
	v_cmp_eq_f32_e64 s[18:19], v7, v0
	v_cmp_lt_u32_e64 s[0:1], s99, v132
	v_cmp_gt_f32_e64 s[16:17], v7, v0
	s_and_b64 s[0:1], s[18:19], s[0:1]
	s_or_b64 s[0:1], s[16:17], s[0:1]
	v_addc_co_u32_e64 v4, s[0:1], 0, v4, s[0:1]
	s_add_i32 s99, s72, 2
	v_cmp_lt_u32_e64 s[14:15], s99, v155
	v_cmp_eq_f32_e64 s[20:21], v8, v1
	v_cmp_gt_f32_e64 s[0:1], v8, v1
	s_and_b64 s[14:15], s[20:21], s[14:15]
	s_or_b64 s[0:1], s[0:1], s[14:15]
	v_addc_co_u32_e64 v3, s[0:1], 0, v3, s[0:1]
	v_cmp_eq_f32_e64 s[18:19], v8, v0
	v_cmp_lt_u32_e64 s[0:1], s99, v132
	v_cmp_gt_f32_e64 s[16:17], v8, v0
	s_and_b64 s[0:1], s[18:19], s[0:1]
	s_or_b64 s[0:1], s[16:17], s[0:1]
	v_addc_co_u32_e64 v4, s[0:1], 0, v4, s[0:1]
	s_add_i32 s99, s72, 3
	v_cmp_lt_u32_e64 s[14:15], s99, v155
	v_cmp_eq_f32_e64 s[20:21], v9, v1
	v_cmp_gt_f32_e64 s[0:1], v9, v1
	s_and_b64 s[14:15], s[20:21], s[14:15]
	s_or_b64 s[0:1], s[0:1], s[14:15]
	v_addc_co_u32_e64 v3, s[0:1], 0, v3, s[0:1]
	v_cmp_eq_f32_e64 s[18:19], v9, v0
	v_cmp_lt_u32_e64 s[0:1], s99, v132
	v_cmp_gt_f32_e64 s[16:17], v9, v0
	s_and_b64 s[0:1], s[18:19], s[0:1]
	s_or_b64 s[0:1], s[16:17], s[0:1]
	v_addc_co_u32_e64 v4, s[0:1], 0, v4, s[0:1]
	s_add_i32 s99, s72, 4
	v_cmp_lt_u32_e64 s[14:15], s99, v155
	v_cmp_eq_f32_e64 s[20:21], v240, v1
	v_cmp_gt_f32_e64 s[0:1], v240, v1
	s_and_b64 s[14:15], s[20:21], s[14:15]
	s_or_b64 s[0:1], s[0:1], s[14:15]
	v_addc_co_u32_e64 v3, s[0:1], 0, v3, s[0:1]
	v_cmp_eq_f32_e64 s[18:19], v240, v0
	v_cmp_lt_u32_e64 s[0:1], s99, v132
	v_cmp_gt_f32_e64 s[16:17], v240, v0
	s_and_b64 s[0:1], s[18:19], s[0:1]
	s_or_b64 s[0:1], s[16:17], s[0:1]
	v_addc_co_u32_e64 v4, s[0:1], 0, v4, s[0:1]
	s_add_i32 s99, s72, 5
	v_cmp_lt_u32_e64 s[14:15], s99, v155
	v_cmp_eq_f32_e64 s[20:21], v241, v1
	v_cmp_gt_f32_e64 s[0:1], v241, v1
	s_and_b64 s[14:15], s[20:21], s[14:15]
	s_or_b64 s[0:1], s[0:1], s[14:15]
	v_addc_co_u32_e64 v3, s[0:1], 0, v3, s[0:1]
	v_cmp_eq_f32_e64 s[18:19], v241, v0
	v_cmp_lt_u32_e64 s[0:1], s99, v132
	v_cmp_gt_f32_e64 s[16:17], v241, v0
	s_and_b64 s[0:1], s[18:19], s[0:1]
	s_or_b64 s[0:1], s[16:17], s[0:1]
	v_addc_co_u32_e64 v4, s[0:1], 0, v4, s[0:1]
	s_add_i32 s99, s72, 6
	v_cmp_lt_u32_e64 s[14:15], s99, v155
	v_cmp_eq_f32_e64 s[20:21], v242, v1
	v_cmp_gt_f32_e64 s[0:1], v242, v1
	s_and_b64 s[14:15], s[20:21], s[14:15]
	s_or_b64 s[0:1], s[0:1], s[14:15]
	v_addc_co_u32_e64 v3, s[0:1], 0, v3, s[0:1]
	v_cmp_eq_f32_e64 s[18:19], v242, v0
	v_cmp_lt_u32_e64 s[0:1], s99, v132
	v_cmp_gt_f32_e64 s[16:17], v242, v0
	s_and_b64 s[0:1], s[18:19], s[0:1]
	s_or_b64 s[0:1], s[16:17], s[0:1]
	v_addc_co_u32_e64 v4, s[0:1], 0, v4, s[0:1]
	s_add_i32 s99, s72, 7
	v_cmp_lt_u32_e64 s[14:15], s99, v155
	v_cmp_eq_f32_e64 s[20:21], v243, v1
	v_cmp_gt_f32_e64 s[0:1], v243, v1
	s_and_b64 s[14:15], s[20:21], s[14:15]
	s_or_b64 s[0:1], s[0:1], s[14:15]
	v_addc_co_u32_e64 v3, s[0:1], 0, v3, s[0:1]
	v_cmp_eq_f32_e64 s[18:19], v243, v0
	v_cmp_lt_u32_e64 s[0:1], s99, v132
	v_cmp_gt_f32_e64 s[16:17], v243, v0
	s_and_b64 s[0:1], s[18:19], s[0:1]
	s_or_b64 s[0:1], s[16:17], s[0:1]
	v_addc_co_u32_e64 v4, s[0:1], 0, v4, s[0:1]
	s_add_i32 s72, s72, 8
	s_branch .Lsel8_1_top

.LBB0_596:
	s_or_b64 exec, exec, s[2:3]
	ds_read2st64_b32 v[0:1], v147 offset0:44 offset1:45
	ds_read2st64_b32 v[4:5], v156 offset0:44 offset1:45
	ds_read2st64_b32 v[6:7], v157 offset0:44 offset1:45
	ds_read2st64_b32 v[8:9], v160 offset0:44 offset1:45
	s_waitcnt lgkmcnt(0)
	v_mov_b32_e32 v10, v1
	v_mov_b32_e32 v11, v0
	v_pk_add_f32 v[0:1], v[10:11], 0 op_sel_hi:[1,0]
	v_mov_b32_e32 v10, v5
	v_mov_b32_e32 v11, v4
	v_pk_add_f32 v[0:1], v[0:1], v[10:11]
	v_mov_b32_e32 v4, v7
	v_mov_b32_e32 v5, v6
	v_pk_add_f32 v[0:1], v[0:1], v[4:5]
	v_mov_b32_e32 v4, v9
	v_mov_b32_e32 v5, v8
	v_pk_add_f32 v[0:1], v[0:1], v[4:5]
	ds_write2st64_b32 v131, v1, v0 offset1:1
	s_and_saveexec_b64 s[2:3], s[12:13]
	s_xor_b64 s[2:3], exec, s[2:3]
	s_cbranch_execz .LBB0_600
	s_mov_b32 s72, 1
	v_mov_b32_e32 v3, 0
	s_mov_b64 s[38:39], 0
	v_mov_b32_e32 v5, v138
	v_mov_b32_e32 v4, 0
	v_readfirstlane_b32 s98, v2
	s_sub_i32 s98, s98, 9

.LBB0_604:
	s_or_b64 exec, exec, s[2:3]
	ds_read2st64_b32 v[0:1], v161 offset0:44 offset1:45
	ds_read2st64_b32 v[4:5], v162 offset0:44 offset1:45
	ds_read2st64_b32 v[6:7], v163 offset0:44 offset1:45
	ds_read2st64_b32 v[8:9], v164 offset0:44 offset1:45
	s_waitcnt lgkmcnt(0)
	v_mov_b32_e32 v10, v1
	v_mov_b32_e32 v11, v0
	v_pk_add_f32 v[0:1], v[10:11], 0 op_sel_hi:[1,0]
	v_mov_b32_e32 v10, v5
	v_mov_b32_e32 v11, v4
	v_pk_add_f32 v[0:1], v[0:1], v[10:11]
	v_mov_b32_e32 v4, v7
	v_mov_b32_e32 v5, v6
	v_pk_add_f32 v[0:1], v[0:1], v[4:5]
	v_mov_b32_e32 v4, v9
	v_mov_b32_e32 v5, v8
	v_pk_add_f32 v[0:1], v[0:1], v[4:5]
	ds_write2st64_b32 v131, v1, v0 offset1:1
	s_and_saveexec_b64 s[2:3], s[12:13]
	s_xor_b64 s[2:3], exec, s[2:3]
	s_cbranch_execz .LBB0_608
	s_mov_b32 s38, 1
	v_mov_b32_e32 v3, 0
	s_mov_b64 s[20:21], 0
	v_mov_b32_e32 v5, v138
	v_mov_b32_e32 v4, 0
	v_readfirstlane_b32 s98, v2
	s_sub_i32 s98, s98, 9
.Lsel8_3_top:
	s_cmp_gt_i32 s38, s98
	s_cbranch_scc1 .LBB0_606
	ds_read2_b32 v[6:7], v5 offset1:1
	ds_read2_b32 v[8:9], v5 offset0:2 offset1:3
	ds_read2_b32 v[240:241], v5 offset0:4 offset1:5
	ds_read2_b32 v[242:243], v5 offset0:6 offset1:7
	v_add_u32_e32 v5, 32, v5
	s_waitcnt lgkmcnt(0)
	v_cmp_lt_u32_e64 s[12:13], s38, v155
	v_cmp_eq_f32_e64 s[18:19], v6, v1
	v_cmp_gt_f32_e64 s[0:1], v6, v1
	s_and_b64 s[12:13], s[18:19], s[12:13]
	s_or_b64 s[0:1], s[0:1], s[12:13]
	v_addc_co_u32_e64 v3, s[0:1], 0, v3, s[0:1]
	v_cmp_eq_f32_e64 s[16:17], v6, v0
	v_cmp_lt_u32_e64 s[0:1], s38, v132
	v_cmp_gt_f32_e64 s[14:15], v6, v0
	s_and_b64 s[0:1], s[16:17], s[0:1]
	s_or_b64 s[0:1], s[14:15], s[0:1]
	v_addc_co_u32_e64 v4, s[0:1], 0, v4, s[0:1]
	s_add_i32 s99, s38, 1
	v_cmp_lt_u32_e64 s[12:13], s99, v155
	v_cmp_eq_f32_e64 s[18:19], v7, v1
	v_cmp_gt_f32_e64 s[0:1], v7, v1
	s_and_b64 s[12:13], s[18:19], s[12:13]
	s_or_b64 s[0:1], s[0:1], s[12:13]
	v_addc_co_u32_e64 v3, s[0:1], 0, v3, s[0:1]
	v_cmp_eq_f32_e64 s[16:17], v7, v0
	v_cmp_lt_u32_e64 s[0:1], s99, v132
	v_cmp_gt_f32_e64 s[14:15], v7, v0
	s_and_b64 s[0:1], s[16:17], s[0:1]
	s_or_b64 s[0:1], s[14:15], s[0:1]
	v_addc_co_u32_e64 v4, s[0:1], 0, v4, s[0:1]
	s_add_i32 s99, s38, 2
	v_cmp_lt_u32_e64 s[12:13], s99, v155
	v_cmp_eq_f32_e64 s[18:19], v8, v1
	v_cmp_gt_f32_e64 s[0:1], v8, v1
	s_and_b64 s[12:13], s[18:19], s[12:13]
	s_or_b64 s[0:1], s[0:1], s[12:13]
	v_addc_co_u32_e64 v3, s[0:1], 0, v3, s[0:1]
	v_cmp_eq_f32_e64 s[16:17], v8, v0
	v_cmp_lt_u32_e64 s[0:1], s99, v132
	v_cmp_gt_f32_e64 s[14:15], v8, v0
	s_and_b64 s[0:1], s[16:17], s[0:1]
	s_or_b64 s[0:1], s[14:15], s[0:1]
	v_addc_co_u32_e64 v4, s[0:1], 0, v4, s[0:1]
	s_add_i32 s99, s38, 3
	v_cmp_lt_u32_e64 s[12:13], s99, v155
	v_cmp_eq_f32_e64 s[18:19], v9, v1
	v_cmp_gt_f32_e64 s[0:1], v9, v1
	s_and_b64 s[12:13], s[18:19], s[12:13]
	s_or_b64 s[0:1], s[0:1], s[12:13]
	v_addc_co_u32_e64 v3, s[0:1], 0, v3, s[0:1]
	v_cmp_eq_f32_e64 s[16:17], v9, v0
	v_cmp_lt_u32_e64 s[0:1], s99, v132
	v_cmp_gt_f32_e64 s[14:15], v9, v0
	s_and_b64 s[0:1], s[16:17], s[0:1]
	s_or_b64 s[0:1], s[14:15], s[0:1]
	v_addc_co_u32_e64 v4, s[0:1], 0, v4, s[0:1]
	s_add_i32 s99, s38, 4
	v_cmp_lt_u32_e64 s[12:13], s99, v155
	v_cmp_eq_f32_e64 s[18:19], v240, v1
	v_cmp_gt_f32_e64 s[0:1], v240, v1
	s_and_b64 s[12:13], s[18:19], s[12:13]
	s_or_b64 s[0:1], s[0:1], s[12:13]
	v_addc_co_u32_e64 v3, s[0:1], 0, v3, s[0:1]
	v_cmp_eq_f32_e64 s[16:17], v240, v0
	v_cmp_lt_u32_e64 s[0:1], s99, v132
	v_cmp_gt_f32_e64 s[14:15], v240, v0
	s_and_b64 s[0:1], s[16:17], s[0:1]
	s_or_b64 s[0:1], s[14:15], s[0:1]
	v_addc_co_u32_e64 v4, s[0:1], 0, v4, s[0:1]
	s_add_i32 s99, s38, 5
	v_cmp_lt_u32_e64 s[12:13], s99, v155
	v_cmp_eq_f32_e64 s[18:19], v241, v1
	v_cmp_gt_f32_e64 s[0:1], v241, v1
	s_and_b64 s[12:13], s[18:19], s[12:13]
	s_or_b64 s[0:1], s[0:1], s[12:13]
	v_addc_co_u32_e64 v3, s[0:1], 0, v3, s[0:1]
	v_cmp_eq_f32_e64 s[16:17], v241, v0
	v_cmp_lt_u32_e64 s[0:1], s99, v132
	v_cmp_gt_f32_e64 s[14:15], v241, v0
	s_and_b64 s[0:1], s[16:17], s[0:1]
	s_or_b64 s[0:1], s[14:15], s[0:1]
	v_addc_co_u32_e64 v4, s[0:1], 0, v4, s[0:1]
	s_add_i32 s99, s38, 6
	v_cmp_lt_u32_e64 s[12:13], s99, v155
	v_cmp_eq_f32_e64 s[18:19], v242, v1
	v_cmp_gt_f32_e64 s[0:1], v242, v1
	s_and_b64 s[12:13], s[18:19], s[12:13]
	s_or_b64 s[0:1], s[0:1], s[12:13]
	v_addc_co_u32_e64 v3, s[0:1], 0, v3, s[0:1]
	v_cmp_eq_f32_e64 s[16:17], v242, v0
	v_cmp_lt_u32_e64 s[0:1], s99, v132
	v_cmp_gt_f32_e64 s[14:15], v242, v0
	s_and_b64 s[0:1], s[16:17], s[0:1]
	s_or_b64 s[0:1], s[14:15], s[0:1]
	v_addc_co_u32_e64 v4, s[0:1], 0, v4, s[0:1]
	s_add_i32 s99, s38, 7
	v_cmp_lt_u32_e64 s[12:13], s99, v155
	v_cmp_eq_f32_e64 s[18:19], v243, v1
	v_cmp_gt_f32_e64 s[0:1], v243, v1
	s_and_b64 s[12:13], s[18:19], s[12:13]
	s_or_b64 s[0:1], s[0:1], s[12:13]
	v_addc_co_u32_e64 v3, s[0:1], 0, v3, s[0:1]
	v_cmp_eq_f32_e64 s[16:17], v243, v0
	v_cmp_lt_u32_e64 s[0:1], s99, v132
	v_cmp_gt_f32_e64 s[14:15], v243, v0
	s_and_b64 s[0:1], s[16:17], s[0:1]
	s_or_b64 s[0:1], s[14:15], s[0:1]
	v_addc_co_u32_e64 v4, s[0:1], 0, v4, s[0:1]
	s_add_i32 s38, s38, 8
	s_branch .Lsel8_3_top

.LBB0_612:
	v_cmp_gt_u32_e32 vcc, 64, v154
	s_waitcnt lgkmcnt(0)
	s_barrier
	s_and_saveexec_b64 s[0:1], vcc
	s_cbranch_execz .LBB0_619
	v_lshlrev_b32_e32 v0, 4, v154
	v_add_u32_e32 v0, 0x14440, v0
	ds_read_b128 v[4:7], v0
	s_waitcnt lgkmcnt(0)
	v_or_b32_dpp v4, v4, v4 quad_perm:[1,0,3,2] row_mask:0xf bank_mask:0xf bound_ctrl:1
	v_or_b32_dpp v5, v5, v5 quad_perm:[1,0,3,2] row_mask:0xf bank_mask:0xf bound_ctrl:1
	v_or_b32_dpp v6, v6, v6 quad_perm:[1,0,3,2] row_mask:0xf bank_mask:0xf bound_ctrl:1
	v_or_b32_dpp v7, v7, v7 quad_perm:[1,0,3,2] row_mask:0xf bank_mask:0xf bound_ctrl:1
	v_or_b32_dpp v4, v4, v4 quad_perm:[2,3,0,1] row_mask:0xf bank_mask:0xf bound_ctrl:1
	v_or_b32_dpp v5, v5, v5 quad_perm:[2,3,0,1] row_mask:0xf bank_mask:0xf bound_ctrl:1
	v_or_b32_dpp v6, v6, v6 quad_perm:[2,3,0,1] row_mask:0xf bank_mask:0xf bound_ctrl:1
	v_or_b32_dpp v7, v7, v7 quad_perm:[2,3,0,1] row_mask:0xf bank_mask:0xf bound_ctrl:1
	v_or_b32_dpp v4, v4, v4 row_half_mirror row_mask:0xf bank_mask:0xf bound_ctrl:1
	v_or_b32_dpp v5, v5, v5 row_half_mirror row_mask:0xf bank_mask:0xf bound_ctrl:1
	v_or_b32_dpp v6, v6, v6 row_half_mirror row_mask:0xf bank_mask:0xf bound_ctrl:1
	v_or_b32_dpp v7, v7, v7 row_half_mirror row_mask:0xf bank_mask:0xf bound_ctrl:1
	v_or_b32_dpp v4, v4, v4 row_mirror row_mask:0xf bank_mask:0xf bound_ctrl:1
	v_or_b32_dpp v5, v5, v5 row_mirror row_mask:0xf bank_mask:0xf bound_ctrl:1
	v_or_b32_dpp v6, v6, v6 row_mirror row_mask:0xf bank_mask:0xf bound_ctrl:1
	v_or_b32_dpp v7, v7, v7 row_mirror row_mask:0xf bank_mask:0xf bound_ctrl:1
	v_readlane_b32 s2, v4, 0
	v_readlane_b32 s3, v5, 0
	v_readlane_b32 s98, v6, 0
	v_readlane_b32 s99, v7, 0
	v_readlane_b32 s7, v4, 16
	s_or_b32 s2, s2, s7
	v_readlane_b32 s7, v5, 16
	s_or_b32 s3, s3, s7
	v_readlane_b32 s7, v6, 16
	s_or_b32 s98, s98, s7
	v_readlane_b32 s7, v7, 16
	s_or_b32 s99, s99, s7
	v_readlane_b32 s7, v4, 32
	s_or_b32 s2, s2, s7
	v_readlane_b32 s7, v5, 32
	s_or_b32 s3, s3, s7
	v_readlane_b32 s7, v6, 32
	s_or_b32 s98, s98, s7
	v_readlane_b32 s7, v7, 32
	s_or_b32 s99, s99, s7
	v_readlane_b32 s7, v4, 48
	s_or_b32 s2, s2, s7
	v_readlane_b32 s7, v5, 48
	s_or_b32 s3, s3, s7
	v_readlane_b32 s7, v6, 48
	s_or_b32 s98, s98, s7
	v_readlane_b32 s7, v7, 48
	s_or_b32 s99, s99, s7
	s_mov_b64 exec, s[2:3]
	v_mbcnt_lo_u32_b32 v1, s2, 0
	v_mbcnt_hi_u32_b32 v1, s3, v1
	v_lshlrev_b32_e32 v1, 2, v1
	v_add_u32_e32 v1, 0x14840, v1
	ds_write_b32 v1, v154
	s_bcnt1_i32_b64 s7, s[2:3]
	s_mov_b64 exec, s[98:99]
	v_mbcnt_lo_u32_b32 v1, s98, 0
	v_mbcnt_hi_u32_b32 v1, s99, v1
	v_add_u32_e32 v1, s7, v1
	v_lshlrev_b32_e32 v1, 2, v1
	v_add_u32_e32 v1, 0x14840, v1
	v_add_u32_e32 v2, 64, v154
	ds_write_b32 v1, v2
	s_bcnt1_i32_b64 s2, s[98:99]
	s_add_i32 s2, s2, s7
	s_mov_b64 exec, -1

.LBB0_797:
	v_readlane_b32 s0, v244, 33
	s_cmp_lg_u32 s0, 0
	s_nop 0
	s_waitcnt vmcnt(0)
	s_waitcnt vmcnt(0) lgkmcnt(0)
	s_barrier
	s_mov_b64 s[0:1], exec
	v_readlane_b32 s2, v246, 4
	v_readlane_b32 s3, v246, 5
	s_and_b64 s[2:3], s[0:1], s[2:3]
	s_mov_b64 exec, s[2:3]
	s_cbranch_execz .LBB0_851
	s_getreg_b32 s2, hwreg(HW_REG_XCC_ID, 0, 4)
	s_waitcnt vmcnt(0) expcnt(0) lgkmcnt(0)
	ds_read_b32 v2, v28 offset:4832
	ds_read_b32 v0, v28 offset:4836
	s_and_b32 s7, s2, 15
	s_waitcnt lgkmcnt(1)
	v_cmp_ne_u32_e32 vcc, 0, v2
	s_cbranch_vccnz .LBB0_815
	s_mov_b32 s10, 1
	s_branch .LBB0_802
